# mixA sliding-window attention: s_setprio 1/0 around the QK and PV MFMA clusters as well (on top of the diff-attention setprio)
# speedup vs baseline: 1.0090x; 1.0019x over previous
; DI size_t PIDX(int row, int col) { return ((size_t)(col >> 8) * S + row) * 256 + (col & 255); }
; DI int crow(int reg, int h) { return (reg & 3) + 8 * (reg >> 2) + 4 * h; }
; #define MFMA32(a, b, c) __builtin_amdgcn_mfma_f32_32x32x16_bf16((a), (b), (c), 0, 0, 0)
; DI void mixA_wave_item(const Params& p, int wi, int lane, const LAS float* tb) {
;     ...
;     for (int kb = 0; kb < 5; ++kb) {
;         const int mk0r = m0 - 64 + 32 * kb;
;         const bool blk_ok = (mk0r >= 0) && (mk0r < n);
;         const int mk0 = blk_ok ? mk0r : m0;
;         bf16x8 vfr[2][4];
; #pragma unroll
;         for (int sidx = 0; sidx < 2; ++sidx)
; #pragma unroll
;             for (int db = 0; db < 4; ++db) {
;                 const bf16_t* vp = vt + (size_t)(32 * db + r) * S + mk0 + 16 * sidx + 4 * hh;
;                 const s16x4 lo = *(const s16x4*)vp, hi = *(const s16x4*)(vp + 8);
;                 vfr[sidx][db] = __builtin_shufflevector(lo, hi, 0, 1, 2, 3, 4, 5, 6, 7);
;             }
;         __builtin_amdgcn_sched_barrier(0);
;         f32x16 s;
; #pragma unroll
;         for (int i = 0; i < 16; ++i) s[i] = 0.f;
; #pragma unroll
;         for (int ks = 0; ks < 8; ++ks) s = MFMA32(kf[ks], qf[ks], s);
;         if (kb < 4) {
;             const int nk0r = m0 - 64 + 32 * (kb + 1); const int nk0 = (nk0r >= 0 && nk0r < n) ? nk0r : m0;
;             const bf16_t* kp = proj + PIDX(((nk0 + r) << sh) + res, g * 3072 + 1024 + h * 128 + 8 * hh);
; #pragma unroll
;             for (int ks = 0; ks < 8; ++ks) kf[ks] = *(const bf16x8*)(kp + 16 * ks);
;         }
;         __builtin_amdgcn_sched_barrier(0);
;         float mx = -INFINITY;
; #pragma unroll
;         for (int i = 0; i < 16; ++i) { const int rel = mk0r + crow(i, hh) - (m0 + r); const bool valid = blk_ok && (rel <= 64) && (rel >= -64);
;             const float bv = tbl[32 * kb + (i & 3) + 8 * (i >> 2)];
;             const float v = valid ? (s[i] * cs + bv) : -INFINITY; s[i] = v; mx = fmaxf(mx, v); }
.LBB0_560:
	v_add_u32_e32 v211, s4, v204
	v_subrev_u32_e32 v64, 64, v211
	v_cmp_lt_i32_e32 vcc, -1, v64
	v_cmp_lt_i32_e64 s[40:41], v64, v205
	s_and_b64 vcc, vcc, s[40:41]
	v_cndmask_b32_e32 v64, v204, v64, vcc
	v_ashrrev_i32_e32 v65, 31, v64
	v_lshl_add_u64 v[64:65], v[64:65], 1, v[190:191]
	v_mov_b32_e32 v195, v97
	v_lshl_add_u64 v[68:69], v[64:65], 0, v[194:195]
	v_mov_b32_e32 v197, v97
	v_mov_b32_e32 v199, v97
	v_lshl_add_u64 v[66:67], v[64:65], 0, v[96:97]
	v_lshl_add_u64 v[70:71], v[64:65], 0, v[196:197]
	global_load_dwordx4 v[170:173], v[68:69], off
	global_load_dwordx4 v[166:169], v[70:71], off
	v_lshl_add_u64 v[68:69], v[64:65], 0, v[198:199]
	v_lshl_add_u64 v[64:65], v[64:65], 0, 32
	global_load_dwordx4 v[174:177], v[66:67], off
	global_load_dwordx4 v[158:161], v[66:67], off offset:32
	v_lshl_add_u64 v[66:67], v[64:65], 0, v[194:195]
	global_load_dwordx4 v[162:165], v[68:69], off
	global_load_dwordx4 v[154:157], v[66:67], off
	v_lshl_add_u64 v[66:67], v[64:65], 0, v[196:197]
	v_lshl_add_u64 v[64:65], v[64:65], 0, v[198:199]
	global_load_dwordx4 v[150:153], v[66:67], off
	global_load_dwordx4 v[146:149], v[64:65], off
	s_waitcnt vmcnt(15)
	s_setprio 1
	v_mfma_f32_32x32x16_bf16 v[64:79], v[114:117], v[80:83], 0
	s_cmpk_eq_i32 s4, 0x80
	s_waitcnt vmcnt(14)
	v_mfma_f32_32x32x16_bf16 v[64:79], v[118:121], v[84:87], v[64:79]
	s_waitcnt vmcnt(13)
	v_mfma_f32_32x32x16_bf16 v[64:79], v[122:125], v[88:91], v[64:79]
	s_waitcnt vmcnt(12)
	v_mfma_f32_32x32x16_bf16 v[64:79], v[126:129], v[92:95], v[64:79]
	s_waitcnt vmcnt(11)
	v_mfma_f32_32x32x16_bf16 v[64:79], v[130:133], v[98:101], v[64:79]
	s_waitcnt vmcnt(10)
	v_mfma_f32_32x32x16_bf16 v[64:79], v[134:137], v[102:105], v[64:79]
	s_waitcnt vmcnt(9)
	v_mfma_f32_32x32x16_bf16 v[64:79], v[138:141], v[106:109], v[64:79]
	s_waitcnt vmcnt(8)
	v_mfma_f32_32x32x16_bf16 v[64:79], v[142:145], v[110:113], v[64:79]
	s_setprio 0
	s_cbranch_scc1 .LBB0_562
	v_subrev_u32_e32 v114, 32, v211
	v_cmp_lt_i32_e64 s[40:41], -1, v114
	v_cmp_lt_i32_e64 s[42:43], v114, v205
	s_and_b64 s[40:41], s[40:41], s[42:43]
	v_cndmask_b32_e64 v114, v204, v114, s[40:41]
	v_or_b32_e32 v114, v114, v206
	v_lshl_add_u32 v114, v114, v185, v203
	v_ashrrev_i32_e32 v115, 31, v114
	v_lshlrev_b64 v[114:115], 9, v[114:115]
	v_lshl_add_u64 v[142:143], v[192:193], 0, v[114:115]
	global_load_dwordx4 v[114:117], v[142:143], off
	global_load_dwordx4 v[118:121], v[142:143], off offset:32
	global_load_dwordx4 v[122:125], v[142:143], off offset:64
	global_load_dwordx4 v[126:129], v[142:143], off offset:96
	global_load_dwordx4 v[130:133], v[142:143], off offset:128
	global_load_dwordx4 v[134:137], v[142:143], off offset:160
	global_load_dwordx4 v[138:141], v[142:143], off offset:192
	s_nop 0
	global_load_dwordx4 v[142:145], v[142:143], off offset:224
.LBB0_562:
	ds_read_b32 v214, v207
	ds_read_b32 v215, v207 offset:4
	ds_read_b32 v216, v207 offset:8
	ds_read_b32 v217, v207 offset:12
	ds_read_b32 v218, v207 offset:32
	ds_read_b32 v219, v207 offset:36
	ds_read_b32 v220, v207 offset:40
	ds_read_b32 v221, v207 offset:44
	ds_read_b32 v234, v207 offset:64
	ds_read_b32 v235, v207 offset:68
	ds_read_b32 v236, v207 offset:72
	ds_read_b32 v237, v207 offset:76
	ds_read_b32 v238, v207 offset:96
	ds_read_b32 v239, v207 offset:100
	ds_read_b32 v246, v207 offset:104
	ds_read_b32 v247, v207 offset:108
	s_waitcnt lgkmcnt(0)
	v_add_u32_e32 v211, s4, v208
	v_cmp_gt_u32_e64 s[40:41], s33, v211
	s_and_b64 s[6:7], vcc, s[40:41]
	v_mov_b32_e32 v195, 0xff800000
	v_mov_b32_e32 v197, 0xff800000
	v_fmac_f32_e32 v214, 0x3e0293ee, v64
	v_cndmask_b32_e64 v197, v197, v214, s[6:7]
	v_add_u32_e32 v64, 1, v211
	v_cmp_gt_u32_e64 s[40:41], s33, v64
	s_and_b64 s[6:7], vcc, s[40:41]
	v_fmac_f32_e32 v215, 0x3e0293ee, v65
	v_cndmask_b32_e64 v195, v195, v215, s[6:7]
	v_add_u32_e32 v64, 2, v211
	v_cmp_gt_u32_e64 s[40:41], s33, v64
	s_and_b64 s[6:7], vcc, s[40:41]
	v_mov_b32_e32 v65, 0xff800000
	v_mov_b32_e32 v199, 0xff800000
	v_fmac_f32_e32 v216, 0x3e0293ee, v66
	v_cndmask_b32_e64 v199, v199, v216, s[6:7]
	v_add_u32_e32 v64, 3, v211
	v_cmp_gt_u32_e64 s[40:41], s33, v64
	s_and_b64 s[6:7], vcc, s[40:41]
	v_fmac_f32_e32 v217, 0x3e0293ee, v67
	v_cndmask_b32_e64 v65, v65, v217, s[6:7]
	v_add_u32_e32 v64, 8, v211
	v_cmp_gt_u32_e64 s[40:41], s33, v64
	s_and_b64 s[6:7], vcc, s[40:41]
	v_mov_b32_e32 v67, 0xff800000
	v_mov_b32_e32 v212, 0xff800000
	v_fmac_f32_e32 v218, 0x3e0293ee, v68
	v_cndmask_b32_e64 v212, v212, v218, s[6:7]
	v_add_u32_e32 v64, 9, v211
	v_cmp_gt_u32_e64 s[40:41], s33, v64
	s_and_b64 s[6:7], vcc, s[40:41]
	v_fmac_f32_e32 v219, 0x3e0293ee, v69
	v_cndmask_b32_e64 v67, v67, v219, s[6:7]
	v_add_u32_e32 v64, 10, v211
	v_cmp_gt_u32_e64 s[40:41], s33, v64
	s_and_b64 s[6:7], vcc, s[40:41]
	v_mov_b32_e32 v68, 0xff800000
	v_mov_b32_e32 v69, 0xff800000
	v_fmac_f32_e32 v220, 0x3e0293ee, v70
	v_cndmask_b32_e64 v69, v69, v220, s[6:7]
	v_add_u32_e32 v64, 11, v211
	v_cmp_gt_u32_e64 s[40:41], s33, v64
	s_and_b64 s[6:7], vcc, s[40:41]
	v_fmac_f32_e32 v221, 0x3e0293ee, v71
	v_cndmask_b32_e64 v68, v68, v221, s[6:7]
	v_add_u32_e32 v64, 16, v211
	v_cmp_gt_u32_e64 s[40:41], s33, v64
	s_and_b64 s[6:7], vcc, s[40:41]
	v_mov_b32_e32 v70, 0xff800000
	v_mov_b32_e32 v71, 0xff800000
	v_fmac_f32_e32 v234, 0x3e0293ee, v72
	v_cndmask_b32_e64 v71, v71, v234, s[6:7]
	v_add_u32_e32 v64, 17, v211
	v_cmp_gt_u32_e64 s[40:41], s33, v64
	s_and_b64 s[6:7], vcc, s[40:41]
	v_fmac_f32_e32 v235, 0x3e0293ee, v73
	v_cndmask_b32_e64 v70, v70, v235, s[6:7]
	v_add_u32_e32 v64, 18, v211
	v_cmp_gt_u32_e64 s[40:41], s33, v64
	s_and_b64 s[6:7], vcc, s[40:41]
	v_mov_b32_e32 v72, 0xff800000
	v_mov_b32_e32 v73, 0xff800000
; DI int crow(int reg, int h) { return (reg & 3) + 8 * (reg >> 2) + 4 * h; }
; #define MFMA32(a, b, c) __builtin_amdgcn_mfma_f32_32x32x16_bf16((a), (b), (c), 0, 0, 0)
; DI void mixA_wave_item(const Params& p, int wi, int lane, const LAS float* tb) {
;     ...
;         for (int i = 0; i < 16; ++i) { const int rel = mk0r + crow(i, hh) - (m0 + r); const bool valid = blk_ok && (rel <= 64) && (rel >= -64);
;             const float bv = tbl[32 * kb + (i & 3) + 8 * (i >> 2)];
;             const float v = valid ? (s[i] * cs + bv) : -INFINITY; s[i] = v; mx = fmaxf(mx, v); }
;         mx = xhalf_max(mx);
;         const float mnew = fmaxf(m, mx), alpha = __builtin_amdgcn_exp2f(m - mnew);
;         m = mnew;
;         float rs = 0.f;
; #pragma unroll
;         for (int i = 0; i < 16; ++i) { s[i] = __builtin_amdgcn_exp2f(s[i] - mnew); rs += s[i]; }
;         lsum = lsum * alpha + rs;
; #pragma unroll
;         for (int db = 0; db < 4; ++db) O[db] *= alpha;
; #pragma unroll
;         for (int sidx = 0; sidx < 2; ++sidx) {
;             const bf16x8 pf = pack8(s, sidx);
; #pragma unroll
;             for (int db = 0; db < 4; ++db) O[db] = MFMA32(vfr[sidx][db], pf, O[db]);
;         }
	v_fmac_f32_e32 v236, 0x3e0293ee, v74
	v_cndmask_b32_e64 v73, v73, v236, s[6:7]
	v_add_u32_e32 v64, 19, v211
	v_cmp_gt_u32_e64 s[40:41], s33, v64
	s_and_b64 s[6:7], vcc, s[40:41]
	v_fmac_f32_e32 v237, 0x3e0293ee, v75
	v_cndmask_b32_e64 v72, v72, v237, s[6:7]
	v_add_u32_e32 v64, 24, v211
	v_cmp_gt_u32_e64 s[40:41], s33, v64
	s_and_b64 s[6:7], vcc, s[40:41]
	v_mov_b32_e32 v74, 0xff800000
	v_mov_b32_e32 v75, 0xff800000
	v_fmac_f32_e32 v238, 0x3e0293ee, v76
	v_cndmask_b32_e64 v75, v75, v238, s[6:7]
	v_add_u32_e32 v64, 25, v211
	v_cmp_gt_u32_e64 s[40:41], s33, v64
	s_and_b64 s[6:7], vcc, s[40:41]
	v_fmac_f32_e32 v239, 0x3e0293ee, v77
	v_cndmask_b32_e64 v74, v74, v239, s[6:7]
	v_add_u32_e32 v64, 26, v211
	v_cmp_gt_u32_e64 s[40:41], s33, v64
	s_and_b64 s[6:7], vcc, s[40:41]
	v_mov_b32_e32 v76, 0xff800000
	v_mov_b32_e32 v77, 0xff800000
	v_fmac_f32_e32 v246, 0x3e0293ee, v78
	v_cndmask_b32_e64 v77, v77, v246, s[6:7]
	v_add_u32_e32 v64, 27, v211
	v_cmp_gt_u32_e64 s[40:41], s33, v64
	s_and_b64 s[6:7], vcc, s[40:41]
	v_fmac_f32_e32 v247, 0x3e0293ee, v79
	v_cndmask_b32_e64 v76, v76, v247, s[6:7]
	s_or_b64 exec, exec, s[16:17]
	s_mov_b32 s5, 0xff800000
	v_max3_f32 v64, v197, s5, v195
	v_max3_f32 v64, v64, v199, v65
	v_max3_f32 v64, v64, v212, v67
	v_max3_f32 v64, v64, v69, v68
	v_max3_f32 v64, v64, v71, v70
	v_max3_f32 v64, v64, v73, v72
	v_max3_f32 v64, v64, v75, v74
	v_max3_f32 v64, v64, v77, v76
	v_mov_b32_e32 v66, v64
	s_nop 1
	v_permlane32_swap_b32_e32 v64, v66
	v_max3_f32 v66, v210, v64, v66
	v_sub_f32_e32 v65, v65, v66
	v_sub_f32_e32 v78, v197, v66
	v_exp_f32_e32 v197, v65
	v_sub_f32_e32 v65, v212, v66
	v_sub_f32_e32 v79, v195, v66
	v_sub_f32_e32 v195, v199, v66
	v_exp_f32_e32 v199, v65
	v_sub_f32_e32 v65, v67, v66
	v_exp_f32_e32 v67, v65
	v_sub_f32_e32 v65, v69, v66
	v_sub_f32_e32 v64, v210, v66
	v_exp_f32_e32 v210, v65
	v_sub_f32_e32 v65, v68, v66
	v_exp_f32_e32 v211, v65
	v_sub_f32_e32 v65, v71, v66
	v_exp_f32_e32 v212, v65
	v_sub_f32_e32 v65, v70, v66
	v_exp_f32_e32 v213, v65
	v_sub_f32_e32 v65, v73, v66
	v_exp_f32_e32 v73, v65
	v_sub_f32_e32 v65, v72, v66
	v_exp_f32_e32 v64, v64
	v_exp_f32_e32 v78, v78
	v_exp_f32_e32 v79, v79
	v_exp_f32_e32 v195, v195
	v_exp_f32_e32 v72, v65
	v_sub_f32_e32 v65, v75, v66
	v_exp_f32_e32 v75, v65
	v_sub_f32_e32 v65, v74, v66
	v_exp_f32_e32 v74, v65
	v_sub_f32_e32 v65, v77, v66
	v_exp_f32_e32 v77, v65
	v_sub_f32_e32 v65, v76, v66
	v_exp_f32_e32 v76, v65
	v_pk_mul_f32 v[62:63], v[62:63], v[64:65] op_sel_hi:[1,0]
	v_pk_mul_f32 v[60:61], v[60:61], v[64:65] op_sel_hi:[1,0]
	v_pk_mul_f32 v[58:59], v[58:59], v[64:65] op_sel_hi:[1,0]
	v_pk_mul_f32 v[56:57], v[56:57], v[64:65] op_sel_hi:[1,0]
	v_pk_mul_f32 v[54:55], v[54:55], v[64:65] op_sel_hi:[1,0]
	v_pk_mul_f32 v[52:53], v[52:53], v[64:65] op_sel_hi:[1,0]
	v_pk_mul_f32 v[50:51], v[50:51], v[64:65] op_sel_hi:[1,0]
	v_pk_mul_f32 v[48:49], v[48:49], v[64:65] op_sel_hi:[1,0]
	v_pk_mul_f32 v[46:47], v[46:47], v[64:65] op_sel_hi:[1,0]
	v_pk_mul_f32 v[44:45], v[44:45], v[64:65] op_sel_hi:[1,0]
	v_pk_mul_f32 v[42:43], v[42:43], v[64:65] op_sel_hi:[1,0]
	v_pk_mul_f32 v[40:41], v[40:41], v[64:65] op_sel_hi:[1,0]
	v_pk_mul_f32 v[38:39], v[38:39], v[64:65] op_sel_hi:[1,0]
	v_pk_mul_f32 v[36:37], v[36:37], v[64:65] op_sel_hi:[1,0]
	v_pk_mul_f32 v[34:35], v[34:35], v[64:65] op_sel_hi:[1,0]
	v_pk_mul_f32 v[32:33], v[32:33], v[64:65] op_sel_hi:[1,0]
	v_pk_mul_f32 v[30:31], v[30:31], v[64:65] op_sel_hi:[1,0]
	v_pk_mul_f32 v[28:29], v[28:29], v[64:65] op_sel_hi:[1,0]
	v_pk_mul_f32 v[26:27], v[26:27], v[64:65] op_sel_hi:[1,0]
	v_pk_mul_f32 v[24:25], v[24:25], v[64:65] op_sel_hi:[1,0]
	v_pk_mul_f32 v[22:23], v[22:23], v[64:65] op_sel_hi:[1,0]
	v_pk_mul_f32 v[20:21], v[20:21], v[64:65] op_sel_hi:[1,0]
	v_pk_mul_f32 v[18:19], v[18:19], v[64:65] op_sel_hi:[1,0]
	v_pk_mul_f32 v[16:17], v[16:17], v[64:65] op_sel_hi:[1,0]
	v_pk_mul_f32 v[14:15], v[14:15], v[64:65] op_sel_hi:[1,0]
	v_pk_mul_f32 v[12:13], v[12:13], v[64:65] op_sel_hi:[1,0]
	v_pk_mul_f32 v[10:11], v[10:11], v[64:65] op_sel_hi:[1,0]
	v_pk_mul_f32 v[8:9], v[8:9], v[64:65] op_sel_hi:[1,0]
	v_pk_mul_f32 v[6:7], v[6:7], v[64:65] op_sel_hi:[1,0]
	v_pk_mul_f32 v[4:5], v[4:5], v[64:65] op_sel_hi:[1,0]
	v_pk_mul_f32 v[2:3], v[2:3], v[64:65] op_sel_hi:[1,0]
	v_pk_mul_f32 v[0:1], v[0:1], v[64:65] op_sel_hi:[1,0]
	v_add_f32_e32 v65, 0, v78
	v_cvt_pk_bf16_f32 v68, v78, v79
	v_cvt_pk_bf16_f32 v69, v195, v197
	v_cvt_pk_bf16_f32 v70, v199, v67
	v_cvt_pk_bf16_f32 v71, v210, v211
	s_waitcnt vmcnt(5)
	v_permlane32_swap_b32_e32 v174, v176
	v_permlane32_swap_b32_e32 v175, v177
	v_permlane32_swap_b32_e32 v170, v172
	v_permlane32_swap_b32_e32 v171, v173
	v_permlane32_swap_b32_e32 v166, v168
	v_permlane32_swap_b32_e32 v167, v169
	v_add_f32_e32 v65, v79, v65
	v_add_f32_e32 v65, v195, v65
	s_setprio 1
	v_mfma_f32_32x32x16_bf16 v[48:63], v[174:177], v[68:71], v[48:63]
	v_add_f32_e32 v65, v197, v65
	v_add_f32_e32 v65, v199, v65
	v_add_f32_e32 v65, v67, v65
	v_add_f32_e32 v65, v210, v65
	v_add_f32_e32 v65, v211, v65
	v_add_f32_e32 v65, v212, v65
	v_add_f32_e32 v65, v213, v65
	v_mfma_f32_32x32x16_bf16 v[32:47], v[170:173], v[68:71], v[32:47]
	v_add_f32_e32 v65, v73, v65
	v_add_f32_e32 v65, v72, v65
	v_add_f32_e32 v65, v75, v65
	v_add_f32_e32 v65, v74, v65
	v_add_f32_e32 v65, v77, v65
	v_add_f32_e32 v65, v76, v65
	s_add_i32 s4, s4, 32
	v_mfma_f32_32x32x16_bf16 v[16:31], v[166:169], v[68:71], v[16:31]
	v_fmac_f32_e32 v65, v209, v64
	v_add_u32_e32 v207, 0x80, v207
	s_cmpk_eq_i32 s4, 0xa0
	s_waitcnt vmcnt(3)
	v_permlane32_swap_b32_e32 v162, v164
	v_permlane32_swap_b32_e32 v163, v165
	v_permlane32_swap_b32_e32 v158, v160
	v_permlane32_swap_b32_e32 v159, v161
	v_mfma_f32_32x32x16_bf16 v[0:15], v[162:165], v[68:71], v[0:15]
	v_cvt_pk_bf16_f32 v68, v212, v213
	v_cvt_pk_bf16_f32 v69, v73, v72
	v_cvt_pk_bf16_f32 v70, v75, v74
	v_cvt_pk_bf16_f32 v71, v77, v76
	s_nop 1
	v_mfma_f32_32x32x16_bf16 v[48:63], v[158:161], v[68:71], v[48:63]
	s_waitcnt vmcnt(2)
	v_permlane32_swap_b32_e32 v154, v156
	v_permlane32_swap_b32_e32 v155, v157
	s_nop 1
	v_mfma_f32_32x32x16_bf16 v[32:47], v[154:157], v[68:71], v[32:47]
	s_waitcnt vmcnt(1)
	v_permlane32_swap_b32_e32 v150, v152
	v_permlane32_swap_b32_e32 v151, v153
	s_nop 1
	v_mfma_f32_32x32x16_bf16 v[16:31], v[150:153], v[68:71], v[16:31]
	s_waitcnt vmcnt(0)
	v_permlane32_swap_b32_e32 v146, v148
	v_permlane32_swap_b32_e32 v147, v149
	s_nop 1
	v_mfma_f32_32x32x16_bf16 v[0:15], v[146:149], v[68:71], v[0:15]
	s_setprio 0
	s_cbranch_scc1 .LBB0_596
	v_mov_b32_e32 v209, v65
	v_mov_b32_e32 v210, v66
	s_branch .LBB0_560
